# v26: GEMM K-loops with ping-pong fragment register sets (next k-substep fragments read under the current MFMA block) and the workgroup barrier moved in front of the last MFMA block
# baseline (speedup 1.0000x reference)
.LBB0_206:
.LBB0_207:
.LBB0_208:
	s_add_i32 s12, s37, -2
	s_and_b32 s12, s12, 2
	s_mul_i32 s12, s12, 0x9000
	s_add_i32 s12, s12, 0
	v_add3_u32 v200, s12, v195, v192
	v_add3_u32 v214, s12, v194, v192
	ds_read_b128 v[160:163], v200
	ds_read_b128 v[168:171], v200 offset:4608
	ds_read_b128 v[172:175], v200 offset:9216
	ds_read_b128 v[176:179], v200 offset:13824
	ds_read_b128 v[164:167], v214 offset:36864
	ds_read_b128 v[180:183], v214 offset:41472
.Lkb_0:
	s_waitcnt lgkmcnt(5)
	s_waitcnt lgkmcnt(1)
	v_mfma_f32_32x32x16_bf16 v[112:127], v[160:163], v[164:167], v[112:127]
	v_mfma_f32_32x32x16_bf16 v[80:95], v[168:171], v[164:167], v[80:95]
	ds_read_b128 v[196:199], v214 offset:36896
	ds_read_b128 v[202:205], v200 offset:32
	ds_read_b128 v[206:209], v200 offset:4640
	ds_read_b128 v[210:213], v200 offset:9248
	ds_read_b128 v[224:227], v200 offset:13856
	ds_read_b128 v[228:231], v214 offset:41504
	v_mfma_f32_32x32x16_bf16 v[48:63], v[172:175], v[164:167], v[48:63]
	v_mfma_f32_32x32x16_bf16 v[16:31], v[176:179], v[164:167], v[16:31]
	s_waitcnt lgkmcnt(6)
	v_mfma_f32_32x32x16_bf16 v[96:111], v[160:163], v[180:183], v[96:111]
	v_mfma_f32_32x32x16_bf16 v[64:79], v[168:171], v[180:183], v[64:79]
	v_mfma_f32_32x32x16_bf16 v[32:47], v[172:175], v[180:183], v[32:47]
	v_mfma_f32_32x32x16_bf16 v[0:15], v[176:179], v[180:183], v[0:15]
	s_waitcnt lgkmcnt(0)
	s_and_b32 s12, s37, 2
	s_mul_i32 s12, s12, 0x9000
	v_add_u32_e32 v215, s12, v193
	s_waitcnt vmcnt(7)
	ds_write_b128 v215, v[128:131]
	s_waitcnt vmcnt(6)
	ds_write_b128 v215, v[132:135] offset:36864
	s_waitcnt vmcnt(5)
	ds_write_b128 v215, v[136:139] offset:9216
	s_waitcnt vmcnt(4)
	ds_write_b128 v215, v[140:143] offset:46080
	s_waitcnt vmcnt(3)
	ds_write_b128 v215, v[144:147] offset:18432
	s_waitcnt vmcnt(2)
	ds_write_b128 v215, v[148:151] offset:55296
	s_waitcnt vmcnt(1)
	ds_write_b128 v215, v[152:155] offset:27648
	s_waitcnt vmcnt(0)
	ds_write_b128 v215, v[156:159] offset:64512
	s_cmpk_gt_i32 s2, 0x680
	s_cbranch_scc1 .Lnl_0
	s_add_u32 s96, s92, s2
	s_addc_u32 s97, s93, s3
	s_add_u32 s98, s94, s2
	s_addc_u32 s99, s95, s3
	global_load_dwordx4 v[128:131], v248, s[96:97] offset:256
	global_load_dwordx4 v[132:135], v248, s[98:99] offset:256
	global_load_dwordx4 v[136:139], v249, s[96:97] offset:256
	global_load_dwordx4 v[140:143], v249, s[98:99] offset:256
	global_load_dwordx4 v[144:147], v250, s[96:97] offset:256
	global_load_dwordx4 v[148:151], v250, s[98:99] offset:256
	global_load_dwordx4 v[152:155], v251, s[96:97] offset:256
	global_load_dwordx4 v[156:159], v251, s[98:99] offset:256
.Lnl_0:
	v_mfma_f32_32x32x16_bf16 v[112:127], v[202:205], v[196:199], v[112:127]
	v_mfma_f32_32x32x16_bf16 v[80:95], v[206:209], v[196:199], v[80:95]
	ds_read_b128 v[160:163], v214 offset:36928
	ds_read_b128 v[168:171], v214 offset:41536
	ds_read_b128 v[172:175], v200 offset:64
	ds_read_b128 v[176:179], v200 offset:4672
	ds_read_b128 v[164:167], v200 offset:9280
	ds_read_b128 v[180:183], v200 offset:13888
	v_mfma_f32_32x32x16_bf16 v[48:63], v[210:213], v[196:199], v[48:63]
	v_mfma_f32_32x32x16_bf16 v[16:31], v[224:227], v[196:199], v[16:31]
	v_mfma_f32_32x32x16_bf16 v[96:111], v[202:205], v[228:231], v[96:111]
	v_mfma_f32_32x32x16_bf16 v[64:79], v[206:209], v[228:231], v[64:79]
	v_mfma_f32_32x32x16_bf16 v[32:47], v[210:213], v[228:231], v[32:47]
	v_mfma_f32_32x32x16_bf16 v[0:15], v[224:227], v[228:231], v[0:15]
	s_waitcnt lgkmcnt(3)
	v_mfma_f32_32x32x16_bf16 v[112:127], v[172:175], v[160:163], v[112:127]
	s_waitcnt lgkmcnt(2)
	v_mfma_f32_32x32x16_bf16 v[80:95], v[176:179], v[160:163], v[80:95]
	ds_read_b128 v[196:199], v214 offset:36960
	ds_read_b128 v[202:205], v214 offset:41568
	ds_read_b128 v[206:209], v200 offset:96
	ds_read_b128 v[210:213], v200 offset:4704
	ds_read_b128 v[224:227], v200 offset:9312
	ds_read_b128 v[228:231], v200 offset:13920
	s_waitcnt lgkmcnt(7)
	v_mfma_f32_32x32x16_bf16 v[48:63], v[164:167], v[160:163], v[48:63]
	s_waitcnt lgkmcnt(6)
	v_mfma_f32_32x32x16_bf16 v[16:31], v[180:183], v[160:163], v[16:31]
	v_mfma_f32_32x32x16_bf16 v[96:111], v[172:175], v[168:171], v[96:111]
	v_mfma_f32_32x32x16_bf16 v[64:79], v[176:179], v[168:171], v[64:79]
	v_mfma_f32_32x32x16_bf16 v[32:47], v[164:167], v[168:171], v[32:47]
	v_mfma_f32_32x32x16_bf16 v[0:15], v[180:183], v[168:171], v[0:15]
	s_waitcnt lgkmcnt(0)
	s_barrier
	s_add_u32 s2, s2, 0x80
	s_addc_u32 s3, s3, 0
	s_add_i32 s37, s37, 2
	s_add_i32 s34, s34, 1
	s_cmpk_lg_i32 s2, 0x800
	s_cbranch_scc0 .Lkl_0
	s_add_i32 s12, s37, -2
	s_and_b32 s12, s12, 2
	s_mul_i32 s12, s12, 0x9000
	s_add_i32 s12, s12, 0
	v_add3_u32 v200, s12, v195, v192
	v_add3_u32 v214, s12, v194, v192
	v_mfma_f32_32x32x16_bf16 v[112:127], v[206:209], v[196:199], v[112:127]
	v_mfma_f32_32x32x16_bf16 v[80:95], v[210:213], v[196:199], v[80:95]
	ds_read_b128 v[160:163], v200
	ds_read_b128 v[168:171], v200 offset:4608
	ds_read_b128 v[172:175], v200 offset:9216
	ds_read_b128 v[176:179], v200 offset:13824
	ds_read_b128 v[164:167], v214 offset:36864
	ds_read_b128 v[180:183], v214 offset:41472
	v_mfma_f32_32x32x16_bf16 v[48:63], v[224:227], v[196:199], v[48:63]
	v_mfma_f32_32x32x16_bf16 v[16:31], v[228:231], v[196:199], v[16:31]
	v_mfma_f32_32x32x16_bf16 v[96:111], v[206:209], v[202:205], v[96:111]
	v_mfma_f32_32x32x16_bf16 v[64:79], v[210:213], v[202:205], v[64:79]
	v_mfma_f32_32x32x16_bf16 v[32:47], v[224:227], v[202:205], v[32:47]
	v_mfma_f32_32x32x16_bf16 v[0:15], v[228:231], v[202:205], v[0:15]
	s_branch .Lkb_0
.Lkl_0:
	v_mfma_f32_32x32x16_bf16 v[112:127], v[206:209], v[196:199], v[112:127]
	v_mfma_f32_32x32x16_bf16 v[80:95], v[210:213], v[196:199], v[80:95]
	v_mfma_f32_32x32x16_bf16 v[48:63], v[224:227], v[196:199], v[48:63]
	v_mfma_f32_32x32x16_bf16 v[16:31], v[228:231], v[196:199], v[16:31]
	v_mfma_f32_32x32x16_bf16 v[96:111], v[206:209], v[202:205], v[96:111]
	v_mfma_f32_32x32x16_bf16 v[64:79], v[210:213], v[202:205], v[64:79]
	v_mfma_f32_32x32x16_bf16 v[32:47], v[224:227], v[202:205], v[32:47]
	v_mfma_f32_32x32x16_bf16 v[0:15], v[228:231], v[202:205], v[0:15]
	s_branch .LBB0_211

.LBB0_214:
.LBB0_215:
.LBB0_216:
	s_add_i32 s12, s35, -2
	s_and_b32 s12, s12, 2
	s_mul_i32 s12, s12, 0x9000
	s_add_i32 s12, s12, 0
	v_add3_u32 v214, s12, v194, v192
	v_add3_u32 v215, s12, v195, v192
	ds_read_b128 v[160:163], v214 offset:36864
	ds_read_b128 v[164:167], v215
	ds_read_b128 v[168:171], v215 offset:4608
	ds_read_b128 v[172:175], v215 offset:9216
	ds_read_b128 v[176:179], v215 offset:13824
	ds_read_b128 v[180:183], v214 offset:41472
.Lkb_1:
	s_waitcnt lgkmcnt(5)
	s_waitcnt lgkmcnt(4)
	v_mfma_f32_32x32x16_bf16 v[112:127], v[160:163], v[164:167], v[112:127]
	s_waitcnt lgkmcnt(3)
	v_mfma_f32_32x32x16_bf16 v[80:95], v[160:163], v[168:171], v[80:95]
	ds_read_b128 v[196:199], v214 offset:36896
	ds_read_b128 v[202:205], v215 offset:32
	ds_read_b128 v[206:209], v215 offset:4640
	ds_read_b128 v[210:213], v215 offset:9248
	ds_read_b128 v[224:227], v215 offset:13856
	ds_read_b128 v[228:231], v214 offset:41504
	s_waitcnt lgkmcnt(8)
	v_mfma_f32_32x32x16_bf16 v[48:63], v[160:163], v[172:175], v[48:63]
	s_waitcnt lgkmcnt(7)
	v_mfma_f32_32x32x16_bf16 v[16:31], v[160:163], v[176:179], v[16:31]
	s_waitcnt lgkmcnt(6)
	v_mfma_f32_32x32x16_bf16 v[96:111], v[180:183], v[164:167], v[96:111]
	v_mfma_f32_32x32x16_bf16 v[64:79], v[180:183], v[168:171], v[64:79]
	v_mfma_f32_32x32x16_bf16 v[32:47], v[180:183], v[172:175], v[32:47]
	v_mfma_f32_32x32x16_bf16 v[0:15], v[180:183], v[176:179], v[0:15]
	s_waitcnt lgkmcnt(0)
	s_and_b32 s12, s35, 2
	s_mul_i32 s12, s12, 0x9000
	v_add_u32_e32 v216, s12, v193
	s_waitcnt vmcnt(7)
	ds_write_b128 v216, v[128:131]
	s_waitcnt vmcnt(6)
	ds_write_b128 v216, v[132:135] offset:36864
	s_waitcnt vmcnt(5)
	ds_write_b128 v216, v[136:139] offset:9216
	s_waitcnt vmcnt(4)
	ds_write_b128 v216, v[140:143] offset:46080
	s_waitcnt vmcnt(3)
	ds_write_b128 v216, v[144:147] offset:18432
	s_waitcnt vmcnt(2)
	ds_write_b128 v216, v[148:151] offset:55296
	s_waitcnt vmcnt(1)
	ds_write_b128 v216, v[152:155] offset:27648
	s_waitcnt vmcnt(0)
	ds_write_b128 v216, v[156:159] offset:64512
	s_cmpk_gt_i32 s2, 0x680
	s_cbranch_scc1 .Lnl_1
	s_add_u32 s96, s92, s2
	s_addc_u32 s97, s93, s3
	s_add_u32 s98, s94, s2
	s_addc_u32 s99, s95, s3
	global_load_dwordx4 v[128:131], v248, s[96:97] offset:256
	global_load_dwordx4 v[132:135], v248, s[98:99] offset:256
	global_load_dwordx4 v[136:139], v249, s[96:97] offset:256
	global_load_dwordx4 v[140:143], v249, s[98:99] offset:256
	global_load_dwordx4 v[144:147], v250, s[96:97] offset:256
	global_load_dwordx4 v[148:151], v250, s[98:99] offset:256
	global_load_dwordx4 v[152:155], v251, s[96:97] offset:256
	global_load_dwordx4 v[156:159], v251, s[98:99] offset:256
.Lnl_1:
	v_mfma_f32_32x32x16_bf16 v[112:127], v[196:199], v[202:205], v[112:127]
	v_mfma_f32_32x32x16_bf16 v[80:95], v[196:199], v[206:209], v[80:95]
	ds_read_b128 v[160:163], v214 offset:36928
	ds_read_b128 v[164:167], v214 offset:41536
	ds_read_b128 v[168:171], v215 offset:64
	ds_read_b128 v[172:175], v215 offset:4672
	ds_read_b128 v[176:179], v215 offset:9280
	ds_read_b128 v[180:183], v215 offset:13888
	v_mfma_f32_32x32x16_bf16 v[48:63], v[196:199], v[210:213], v[48:63]
	v_mfma_f32_32x32x16_bf16 v[16:31], v[196:199], v[224:227], v[16:31]
	v_mfma_f32_32x32x16_bf16 v[96:111], v[228:231], v[202:205], v[96:111]
	v_mfma_f32_32x32x16_bf16 v[64:79], v[228:231], v[206:209], v[64:79]
	v_mfma_f32_32x32x16_bf16 v[32:47], v[228:231], v[210:213], v[32:47]
	v_mfma_f32_32x32x16_bf16 v[0:15], v[228:231], v[224:227], v[0:15]
	s_waitcnt lgkmcnt(5)
	s_waitcnt lgkmcnt(3)
	v_mfma_f32_32x32x16_bf16 v[112:127], v[160:163], v[168:171], v[112:127]
	s_waitcnt lgkmcnt(2)
	v_mfma_f32_32x32x16_bf16 v[80:95], v[160:163], v[172:175], v[80:95]
	ds_read_b128 v[196:199], v214 offset:36960
	ds_read_b128 v[202:205], v214 offset:41568
	ds_read_b128 v[206:209], v215 offset:96
	ds_read_b128 v[210:213], v215 offset:4704
	ds_read_b128 v[224:227], v215 offset:9312
	ds_read_b128 v[228:231], v215 offset:13920
	s_waitcnt lgkmcnt(7)
	v_mfma_f32_32x32x16_bf16 v[48:63], v[160:163], v[176:179], v[48:63]
	s_waitcnt lgkmcnt(6)
	v_mfma_f32_32x32x16_bf16 v[16:31], v[160:163], v[180:183], v[16:31]
	v_mfma_f32_32x32x16_bf16 v[96:111], v[164:167], v[168:171], v[96:111]
	v_mfma_f32_32x32x16_bf16 v[64:79], v[164:167], v[172:175], v[64:79]
	v_mfma_f32_32x32x16_bf16 v[32:47], v[164:167], v[176:179], v[32:47]
	v_mfma_f32_32x32x16_bf16 v[0:15], v[164:167], v[180:183], v[0:15]
	s_waitcnt lgkmcnt(0)
	s_barrier
	s_add_u32 s2, s2, 0x80
	s_addc_u32 s3, s3, 0
	s_add_i32 s35, s35, 2
	s_add_i32 s22, s22, 1
	s_cmpk_lg_i32 s2, 0x800
	s_cbranch_scc0 .Lkl_1
	s_add_i32 s12, s35, -2
	s_and_b32 s12, s12, 2
	s_mul_i32 s12, s12, 0x9000
	s_add_i32 s12, s12, 0
	v_add3_u32 v214, s12, v194, v192
	v_add3_u32 v215, s12, v195, v192
	v_mfma_f32_32x32x16_bf16 v[112:127], v[196:199], v[206:209], v[112:127]
	v_mfma_f32_32x32x16_bf16 v[80:95], v[196:199], v[210:213], v[80:95]
	ds_read_b128 v[160:163], v214 offset:36864
	ds_read_b128 v[164:167], v215
	ds_read_b128 v[168:171], v215 offset:4608
	ds_read_b128 v[172:175], v215 offset:9216
	ds_read_b128 v[176:179], v215 offset:13824
	ds_read_b128 v[180:183], v214 offset:41472
	v_mfma_f32_32x32x16_bf16 v[48:63], v[196:199], v[224:227], v[48:63]
	v_mfma_f32_32x32x16_bf16 v[16:31], v[196:199], v[228:231], v[16:31]
	v_mfma_f32_32x32x16_bf16 v[96:111], v[202:205], v[206:209], v[96:111]
	v_mfma_f32_32x32x16_bf16 v[64:79], v[202:205], v[210:213], v[64:79]
	v_mfma_f32_32x32x16_bf16 v[32:47], v[202:205], v[224:227], v[32:47]
	v_mfma_f32_32x32x16_bf16 v[0:15], v[202:205], v[228:231], v[0:15]
	s_branch .Lkb_1
.Lkl_1:
	v_mfma_f32_32x32x16_bf16 v[112:127], v[196:199], v[206:209], v[112:127]
	v_mfma_f32_32x32x16_bf16 v[80:95], v[196:199], v[210:213], v[80:95]
	v_mfma_f32_32x32x16_bf16 v[48:63], v[196:199], v[224:227], v[48:63]
	v_mfma_f32_32x32x16_bf16 v[16:31], v[196:199], v[228:231], v[16:31]
	v_mfma_f32_32x32x16_bf16 v[96:111], v[202:205], v[206:209], v[96:111]
	v_mfma_f32_32x32x16_bf16 v[64:79], v[202:205], v[210:213], v[64:79]
	v_mfma_f32_32x32x16_bf16 v[32:47], v[202:205], v[224:227], v[32:47]
	v_mfma_f32_32x32x16_bf16 v[0:15], v[202:205], v[228:231], v[0:15]
	s_branch .LBB0_202

.LBB0_446:
.LBB0_447:
.LBB0_448:
	s_add_i32 s12, s36, -2
	s_and_b32 s12, s12, 2
	s_mul_i32 s12, s12, 0x9000
	s_add_i32 s12, s12, 0
	v_add3_u32 v193, s12, v192, v188
	v_add3_u32 v197, s12, v191, v188
	ds_read_b128 v[160:163], v193
	ds_read_b128 v[168:171], v193 offset:4608
	ds_read_b128 v[172:175], v193 offset:9216
	ds_read_b128 v[176:179], v193 offset:13824
	ds_read_b128 v[164:167], v197 offset:36864
	ds_read_b128 v[180:183], v197 offset:41472
.Lkb_2:
	s_waitcnt lgkmcnt(5)
	s_waitcnt lgkmcnt(1)
	v_mfma_f32_32x32x16_bf16 v[32:47], v[160:163], v[164:167], v[32:47]
	v_mfma_f32_32x32x16_bf16 v[64:79], v[168:171], v[164:167], v[64:79]
	ds_read_b128 v[202:205], v197 offset:36896
	ds_read_b128 v[206:209], v193 offset:32
	ds_read_b128 v[210:213], v193 offset:4640
	ds_read_b128 v[214:217], v193 offset:9248
	ds_read_b128 v[224:227], v193 offset:13856
	ds_read_b128 v[228:231], v197 offset:41504
	v_mfma_f32_32x32x16_bf16 v[96:111], v[172:175], v[164:167], v[96:111]
	v_mfma_f32_32x32x16_bf16 v[112:127], v[176:179], v[164:167], v[112:127]
	s_waitcnt lgkmcnt(6)
	v_mfma_f32_32x32x16_bf16 v[0:15], v[160:163], v[180:183], v[0:15]
	v_mfma_f32_32x32x16_bf16 v[16:31], v[168:171], v[180:183], v[16:31]
	v_mfma_f32_32x32x16_bf16 v[48:63], v[172:175], v[180:183], v[48:63]
	v_mfma_f32_32x32x16_bf16 v[80:95], v[176:179], v[180:183], v[80:95]
	s_waitcnt lgkmcnt(0)
	s_and_b32 s12, s36, 2
	s_mul_i32 s12, s12, 0x9000
	v_add_u32_e32 v198, s12, v190
	s_waitcnt vmcnt(7)
	ds_write_b128 v198, v[128:131]
	s_waitcnt vmcnt(6)
	ds_write_b128 v198, v[132:135] offset:36864
	s_waitcnt vmcnt(5)
	ds_write_b128 v198, v[136:139] offset:9216
	s_waitcnt vmcnt(4)
	ds_write_b128 v198, v[140:143] offset:46080
	s_waitcnt vmcnt(3)
	ds_write_b128 v198, v[144:147] offset:18432
	s_waitcnt vmcnt(2)
	ds_write_b128 v198, v[148:151] offset:55296
	s_waitcnt vmcnt(1)
	ds_write_b128 v198, v[152:155] offset:27648
	s_waitcnt vmcnt(0)
	ds_write_b128 v198, v[156:159] offset:64512
	s_cmpk_gt_i32 s2, 0x680
	s_cbranch_scc1 .Lnl_2
	s_add_u32 s96, s92, s2
	s_addc_u32 s97, s93, s3
	s_add_u32 s98, s94, s2
	s_addc_u32 s99, s95, s3
	global_load_dwordx4 v[128:131], v248, s[96:97] offset:256
	global_load_dwordx4 v[132:135], v248, s[98:99] offset:256
	global_load_dwordx4 v[136:139], v249, s[96:97] offset:256
	global_load_dwordx4 v[140:143], v249, s[98:99] offset:256
	global_load_dwordx4 v[144:147], v250, s[96:97] offset:256
	global_load_dwordx4 v[148:151], v250, s[98:99] offset:256
	global_load_dwordx4 v[152:155], v251, s[96:97] offset:256
	global_load_dwordx4 v[156:159], v251, s[98:99] offset:256
.Lnl_2:
	v_mfma_f32_32x32x16_bf16 v[32:47], v[206:209], v[202:205], v[32:47]
	v_mfma_f32_32x32x16_bf16 v[64:79], v[210:213], v[202:205], v[64:79]
	ds_read_b128 v[160:163], v197 offset:36928
	ds_read_b128 v[168:171], v197 offset:41536
	ds_read_b128 v[172:175], v193 offset:64
	ds_read_b128 v[176:179], v193 offset:4672
	ds_read_b128 v[164:167], v193 offset:9280
	ds_read_b128 v[180:183], v193 offset:13888
	v_mfma_f32_32x32x16_bf16 v[96:111], v[214:217], v[202:205], v[96:111]
	v_mfma_f32_32x32x16_bf16 v[112:127], v[224:227], v[202:205], v[112:127]
	v_mfma_f32_32x32x16_bf16 v[0:15], v[206:209], v[228:231], v[0:15]
	v_mfma_f32_32x32x16_bf16 v[16:31], v[210:213], v[228:231], v[16:31]
	v_mfma_f32_32x32x16_bf16 v[48:63], v[214:217], v[228:231], v[48:63]
	v_mfma_f32_32x32x16_bf16 v[80:95], v[224:227], v[228:231], v[80:95]
	s_waitcnt lgkmcnt(3)
	v_mfma_f32_32x32x16_bf16 v[32:47], v[172:175], v[160:163], v[32:47]
	s_waitcnt lgkmcnt(2)
	v_mfma_f32_32x32x16_bf16 v[64:79], v[176:179], v[160:163], v[64:79]
	ds_read_b128 v[202:205], v197 offset:36960
	ds_read_b128 v[206:209], v197 offset:41568
	ds_read_b128 v[210:213], v193 offset:96
	ds_read_b128 v[214:217], v193 offset:4704
	ds_read_b128 v[224:227], v193 offset:9312
	ds_read_b128 v[228:231], v193 offset:13920
	s_waitcnt lgkmcnt(7)
	v_mfma_f32_32x32x16_bf16 v[96:111], v[164:167], v[160:163], v[96:111]
	s_waitcnt lgkmcnt(6)
	v_mfma_f32_32x32x16_bf16 v[112:127], v[180:183], v[160:163], v[112:127]
	v_mfma_f32_32x32x16_bf16 v[0:15], v[172:175], v[168:171], v[0:15]
	v_mfma_f32_32x32x16_bf16 v[16:31], v[176:179], v[168:171], v[16:31]
	v_mfma_f32_32x32x16_bf16 v[48:63], v[164:167], v[168:171], v[48:63]
	v_mfma_f32_32x32x16_bf16 v[80:95], v[180:183], v[168:171], v[80:95]
	s_waitcnt lgkmcnt(0)
	s_barrier
	s_add_u32 s2, s2, 0x80
	s_addc_u32 s3, s3, 0
	s_add_i32 s36, s36, 2
	s_add_i32 s4, s4, 1
	s_cmpk_eq_i32 s2, 0x800
	s_cbranch_scc1 .Lkl_2
	s_add_i32 s12, s36, -2
	s_and_b32 s12, s12, 2
	s_mul_i32 s12, s12, 0x9000
	s_add_i32 s12, s12, 0
	v_add3_u32 v193, s12, v192, v188
	v_add3_u32 v197, s12, v191, v188
	v_mfma_f32_32x32x16_bf16 v[32:47], v[210:213], v[202:205], v[32:47]
	v_mfma_f32_32x32x16_bf16 v[64:79], v[214:217], v[202:205], v[64:79]
	ds_read_b128 v[160:163], v193
	ds_read_b128 v[168:171], v193 offset:4608
	ds_read_b128 v[172:175], v193 offset:9216
	ds_read_b128 v[176:179], v193 offset:13824
	ds_read_b128 v[164:167], v197 offset:36864
	ds_read_b128 v[180:183], v197 offset:41472
	v_mfma_f32_32x32x16_bf16 v[96:111], v[224:227], v[202:205], v[96:111]
	v_mfma_f32_32x32x16_bf16 v[112:127], v[228:231], v[202:205], v[112:127]
	v_mfma_f32_32x32x16_bf16 v[0:15], v[210:213], v[206:209], v[0:15]
	v_mfma_f32_32x32x16_bf16 v[16:31], v[214:217], v[206:209], v[16:31]
	v_mfma_f32_32x32x16_bf16 v[48:63], v[224:227], v[206:209], v[48:63]
	v_mfma_f32_32x32x16_bf16 v[80:95], v[228:231], v[206:209], v[80:95]
	s_branch .Lkb_2
.Lkl_2:
	v_mfma_f32_32x32x16_bf16 v[32:47], v[210:213], v[202:205], v[32:47]
	v_mfma_f32_32x32x16_bf16 v[64:79], v[214:217], v[202:205], v[64:79]
	v_mfma_f32_32x32x16_bf16 v[96:111], v[224:227], v[202:205], v[96:111]
	v_mfma_f32_32x32x16_bf16 v[112:127], v[228:231], v[202:205], v[112:127]
	v_mfma_f32_32x32x16_bf16 v[0:15], v[210:213], v[206:209], v[0:15]
	v_mfma_f32_32x32x16_bf16 v[16:31], v[214:217], v[206:209], v[16:31]
	v_mfma_f32_32x32x16_bf16 v[48:63], v[224:227], v[206:209], v[48:63]
	v_mfma_f32_32x32x16_bf16 v[80:95], v[228:231], v[206:209], v[80:95]
	s_branch .LBB0_451

.LBB0_458:
.LBB0_459:
.LBB0_460:
	s_add_i32 s12, s5, -2
	s_and_b32 s12, s12, 2
	s_mul_i32 s12, s12, 0x9000
	s_add_i32 s12, s12, 0
	v_add3_u32 v195, s12, v192, v194
	v_add3_u32 v200, s12, v193, v194
	ds_read_b128 v[160:163], v195 offset:36864
	ds_read_b128 v[164:167], v200
	ds_read_b128 v[168:171], v200 offset:4608
	ds_read_b128 v[172:175], v200 offset:9216
	ds_read_b128 v[176:179], v200 offset:13824
	ds_read_b128 v[180:183], v195 offset:41472
.Lkb_3:
	s_waitcnt lgkmcnt(5)
	s_waitcnt lgkmcnt(4)
	v_mfma_f32_32x32x16_bf16 v[112:127], v[160:163], v[164:167], v[112:127]
	s_waitcnt lgkmcnt(3)
	v_mfma_f32_32x32x16_bf16 v[96:111], v[160:163], v[168:171], v[96:111]
	ds_read_b128 v[196:199], v195 offset:36896
	ds_read_b128 v[202:205], v200 offset:32
	ds_read_b128 v[210:213], v200 offset:4640
	ds_read_b128 v[216:219], v200 offset:9248
	ds_read_b128 v[224:227], v200 offset:13856
	ds_read_b128 v[228:231], v195 offset:41504
	s_waitcnt lgkmcnt(8)
	v_mfma_f32_32x32x16_bf16 v[80:95], v[160:163], v[172:175], v[80:95]
	s_waitcnt lgkmcnt(7)
	v_mfma_f32_32x32x16_bf16 v[48:63], v[160:163], v[176:179], v[48:63]
	s_waitcnt lgkmcnt(6)
	v_mfma_f32_32x32x16_bf16 v[64:79], v[180:183], v[164:167], v[64:79]
	v_mfma_f32_32x32x16_bf16 v[32:47], v[180:183], v[168:171], v[32:47]
	v_mfma_f32_32x32x16_bf16 v[16:31], v[180:183], v[172:175], v[16:31]
	v_mfma_f32_32x32x16_bf16 v[0:15], v[180:183], v[176:179], v[0:15]
	s_waitcnt lgkmcnt(0)
	s_and_b32 s12, s5, 2
	s_mul_i32 s12, s12, 0x9000
	v_add_u32_e32 v206, s12, v185
	s_waitcnt vmcnt(7)
	ds_write_b128 v206, v[128:131]
	s_waitcnt vmcnt(6)
	ds_write_b128 v206, v[132:135] offset:36864
	s_waitcnt vmcnt(5)
	ds_write_b128 v206, v[136:139] offset:9216
	s_waitcnt vmcnt(4)
	ds_write_b128 v206, v[140:143] offset:46080
	s_waitcnt vmcnt(3)
	ds_write_b128 v206, v[144:147] offset:18432
	s_waitcnt vmcnt(2)
	ds_write_b128 v206, v[148:151] offset:55296
	s_waitcnt vmcnt(1)
	ds_write_b128 v206, v[152:155] offset:27648
	s_waitcnt vmcnt(0)
	ds_write_b128 v206, v[156:159] offset:64512
	s_cmpk_gt_i32 s2, 0x680
	s_cbranch_scc1 .Lnl_3
	s_add_u32 s96, s92, s2
	s_addc_u32 s97, s93, s3
	s_add_u32 s98, s94, s2
	s_addc_u32 s99, s95, s3
	global_load_dwordx4 v[128:131], v248, s[96:97] offset:256
	global_load_dwordx4 v[132:135], v248, s[98:99] offset:256
	global_load_dwordx4 v[136:139], v249, s[96:97] offset:256
	global_load_dwordx4 v[140:143], v249, s[98:99] offset:256
	global_load_dwordx4 v[144:147], v250, s[96:97] offset:256
	global_load_dwordx4 v[148:151], v250, s[98:99] offset:256
	global_load_dwordx4 v[152:155], v251, s[96:97] offset:256
	global_load_dwordx4 v[156:159], v251, s[98:99] offset:256
.Lnl_3:
	v_mfma_f32_32x32x16_bf16 v[112:127], v[196:199], v[202:205], v[112:127]
	v_mfma_f32_32x32x16_bf16 v[96:111], v[196:199], v[210:213], v[96:111]
	ds_read_b128 v[160:163], v195 offset:36928
	ds_read_b128 v[164:167], v195 offset:41536
	ds_read_b128 v[168:171], v200 offset:64
	ds_read_b128 v[172:175], v200 offset:4672
	ds_read_b128 v[176:179], v200 offset:9280
	ds_read_b128 v[180:183], v200 offset:13888
	v_mfma_f32_32x32x16_bf16 v[80:95], v[196:199], v[216:219], v[80:95]
	v_mfma_f32_32x32x16_bf16 v[48:63], v[196:199], v[224:227], v[48:63]
	v_mfma_f32_32x32x16_bf16 v[64:79], v[228:231], v[202:205], v[64:79]
	v_mfma_f32_32x32x16_bf16 v[32:47], v[228:231], v[210:213], v[32:47]
	v_mfma_f32_32x32x16_bf16 v[16:31], v[228:231], v[216:219], v[16:31]
	v_mfma_f32_32x32x16_bf16 v[0:15], v[228:231], v[224:227], v[0:15]
	s_waitcnt lgkmcnt(5)
	s_waitcnt lgkmcnt(3)
	v_mfma_f32_32x32x16_bf16 v[112:127], v[160:163], v[168:171], v[112:127]
	s_waitcnt lgkmcnt(2)
	v_mfma_f32_32x32x16_bf16 v[96:111], v[160:163], v[172:175], v[96:111]
	ds_read_b128 v[196:199], v195 offset:36960
	ds_read_b128 v[202:205], v195 offset:41568
	ds_read_b128 v[210:213], v200 offset:96
	ds_read_b128 v[216:219], v200 offset:4704
	ds_read_b128 v[224:227], v200 offset:9312
	ds_read_b128 v[228:231], v200 offset:13920
	s_waitcnt lgkmcnt(7)
	v_mfma_f32_32x32x16_bf16 v[80:95], v[160:163], v[176:179], v[80:95]
	s_waitcnt lgkmcnt(6)
	v_mfma_f32_32x32x16_bf16 v[48:63], v[160:163], v[180:183], v[48:63]
	v_mfma_f32_32x32x16_bf16 v[64:79], v[164:167], v[168:171], v[64:79]
	v_mfma_f32_32x32x16_bf16 v[32:47], v[164:167], v[172:175], v[32:47]
	v_mfma_f32_32x32x16_bf16 v[16:31], v[164:167], v[176:179], v[16:31]
	v_mfma_f32_32x32x16_bf16 v[0:15], v[164:167], v[180:183], v[0:15]
	s_waitcnt lgkmcnt(0)
	s_barrier
	s_add_u32 s2, s2, 0x80
	s_addc_u32 s3, s3, 0
	s_add_i32 s5, s5, 2
	s_add_i32 s4, s4, 1
	s_cmpk_eq_i32 s2, 0x800
	s_cbranch_scc1 .Lkl_3
	s_add_i32 s12, s5, -2
	s_and_b32 s12, s12, 2
	s_mul_i32 s12, s12, 0x9000
	s_add_i32 s12, s12, 0
	v_add3_u32 v195, s12, v192, v194
	v_add3_u32 v200, s12, v193, v194
	v_mfma_f32_32x32x16_bf16 v[112:127], v[196:199], v[210:213], v[112:127]
	v_mfma_f32_32x32x16_bf16 v[96:111], v[196:199], v[216:219], v[96:111]
	ds_read_b128 v[160:163], v195 offset:36864
	ds_read_b128 v[164:167], v200
	ds_read_b128 v[168:171], v200 offset:4608
	ds_read_b128 v[172:175], v200 offset:9216
	ds_read_b128 v[176:179], v200 offset:13824
	ds_read_b128 v[180:183], v195 offset:41472
	v_mfma_f32_32x32x16_bf16 v[80:95], v[196:199], v[224:227], v[80:95]
	v_mfma_f32_32x32x16_bf16 v[48:63], v[196:199], v[228:231], v[48:63]
	v_mfma_f32_32x32x16_bf16 v[64:79], v[202:205], v[210:213], v[64:79]
	v_mfma_f32_32x32x16_bf16 v[32:47], v[202:205], v[216:219], v[32:47]
	v_mfma_f32_32x32x16_bf16 v[16:31], v[202:205], v[224:227], v[16:31]
	v_mfma_f32_32x32x16_bf16 v[0:15], v[202:205], v[228:231], v[0:15]
	s_branch .Lkb_3
.Lkl_3:
	v_mfma_f32_32x32x16_bf16 v[112:127], v[196:199], v[210:213], v[112:127]
	v_mfma_f32_32x32x16_bf16 v[96:111], v[196:199], v[216:219], v[96:111]
	v_mfma_f32_32x32x16_bf16 v[80:95], v[196:199], v[224:227], v[80:95]
	v_mfma_f32_32x32x16_bf16 v[48:63], v[196:199], v[228:231], v[48:63]
	v_mfma_f32_32x32x16_bf16 v[64:79], v[202:205], v[210:213], v[64:79]
	v_mfma_f32_32x32x16_bf16 v[32:47], v[202:205], v[216:219], v[32:47]
	v_mfma_f32_32x32x16_bf16 v[16:31], v[202:205], v[224:227], v[16:31]
	v_mfma_f32_32x32x16_bf16 v[0:15], v[202:205], v[228:231], v[0:15]
	s_branch .LBB0_463

.LBB0_638:
.LBB0_639:
.LBB0_640:
	s_and_b32 s12, s38, 2
	s_mul_i32 s12, s12, 0x9000
	s_add_i32 s12, s12, 0
	v_add3_u32 v197, s12, v196, v195
	v_add3_u32 v198, s12, v194, v195
	ds_read_b128 v[160:163], v197 offset:36864
	ds_read_b128 v[164:167], v198
	ds_read_b128 v[168:171], v198 offset:4608
	ds_read_b128 v[172:175], v198 offset:9216
	ds_read_b128 v[176:179], v198 offset:13824
	ds_read_b128 v[180:183], v197 offset:41472
.Lkb_4:
	s_waitcnt lgkmcnt(5)
	s_waitcnt lgkmcnt(4)
	v_mfma_f32_32x32x16_bf16 v[112:127], v[160:163], v[164:167], v[112:127]
	s_waitcnt lgkmcnt(3)
	v_mfma_f32_32x32x16_bf16 v[80:95], v[160:163], v[168:171], v[80:95]
	ds_read_b128 v[202:205], v197 offset:36896
	ds_read_b128 v[206:209], v198 offset:32
	ds_read_b128 v[210:213], v198 offset:4640
	ds_read_b128 v[214:217], v198 offset:9248
	ds_read_b128 v[224:227], v198 offset:13856
	ds_read_b128 v[228:231], v197 offset:41504
	s_waitcnt lgkmcnt(8)
	v_mfma_f32_32x32x16_bf16 v[48:63], v[160:163], v[172:175], v[48:63]
	s_waitcnt lgkmcnt(7)
	v_mfma_f32_32x32x16_bf16 v[16:31], v[160:163], v[176:179], v[16:31]
	s_waitcnt lgkmcnt(6)
	v_mfma_f32_32x32x16_bf16 v[96:111], v[180:183], v[164:167], v[96:111]
	v_mfma_f32_32x32x16_bf16 v[64:79], v[180:183], v[168:171], v[64:79]
	v_mfma_f32_32x32x16_bf16 v[32:47], v[180:183], v[172:175], v[32:47]
	v_mfma_f32_32x32x16_bf16 v[0:15], v[180:183], v[176:179], v[0:15]
	s_waitcnt lgkmcnt(0)
	s_add_i32 s38, s38, 2
	s_and_b32 s12, s38, 2
	s_mul_i32 s12, s12, 0x9000
	v_add_u32_e32 v199, s12, v193
	s_waitcnt vmcnt(0)
	ds_write_b128 v199, v[128:131]
	ds_write_b128 v199, v[132:135] offset:36864
	ds_write_b128 v199, v[136:139] offset:9216
	ds_write_b128 v199, v[140:143] offset:46080
	ds_write_b128 v199, v[144:147] offset:18432
	ds_write_b128 v199, v[148:151] offset:55296
	ds_write_b128 v199, v[152:155] offset:27648
	ds_write_b128 v199, v[156:159] offset:64512
	s_cmpk_gt_i32 s2, 0x680
	s_cbranch_scc1 .Lnl_7
	s_add_u32 s96, s92, s2
	s_addc_u32 s97, s93, s3
	s_add_u32 s98, s94, s2
	s_addc_u32 s99, s95, s3
	global_load_dwordx4 v[128:131], v248, s[96:97] offset:256
	global_load_dwordx4 v[132:135], v248, s[98:99] offset:256
	global_load_dwordx4 v[136:139], v249, s[96:97] offset:256
	global_load_dwordx4 v[140:143], v249, s[98:99] offset:256
	global_load_dwordx4 v[144:147], v250, s[96:97] offset:256
	global_load_dwordx4 v[148:151], v250, s[98:99] offset:256
	global_load_dwordx4 v[152:155], v251, s[96:97] offset:256
	global_load_dwordx4 v[156:159], v251, s[98:99] offset:256
.Lnl_7:
	v_mfma_f32_32x32x16_bf16 v[112:127], v[202:205], v[206:209], v[112:127]
	v_mfma_f32_32x32x16_bf16 v[80:95], v[202:205], v[210:213], v[80:95]
	ds_read_b128 v[160:163], v197 offset:36928
	ds_read_b128 v[164:167], v197 offset:41536
	ds_read_b128 v[168:171], v198 offset:64
	ds_read_b128 v[172:175], v198 offset:4672
	ds_read_b128 v[176:179], v198 offset:9280
	ds_read_b128 v[180:183], v198 offset:13888
	v_mfma_f32_32x32x16_bf16 v[48:63], v[202:205], v[214:217], v[48:63]
	v_mfma_f32_32x32x16_bf16 v[16:31], v[202:205], v[224:227], v[16:31]
	v_mfma_f32_32x32x16_bf16 v[96:111], v[228:231], v[206:209], v[96:111]
	v_mfma_f32_32x32x16_bf16 v[64:79], v[228:231], v[210:213], v[64:79]
	v_mfma_f32_32x32x16_bf16 v[32:47], v[228:231], v[214:217], v[32:47]
	v_mfma_f32_32x32x16_bf16 v[0:15], v[228:231], v[224:227], v[0:15]
	s_waitcnt lgkmcnt(5)
	s_waitcnt lgkmcnt(3)
	v_mfma_f32_32x32x16_bf16 v[112:127], v[160:163], v[168:171], v[112:127]
	s_waitcnt lgkmcnt(2)
	v_mfma_f32_32x32x16_bf16 v[80:95], v[160:163], v[172:175], v[80:95]
	ds_read_b128 v[202:205], v197 offset:36960
	ds_read_b128 v[206:209], v197 offset:41568
	ds_read_b128 v[210:213], v198 offset:96
	ds_read_b128 v[214:217], v198 offset:4704
	ds_read_b128 v[224:227], v198 offset:9312
	ds_read_b128 v[228:231], v198 offset:13920
	s_waitcnt lgkmcnt(7)
	v_mfma_f32_32x32x16_bf16 v[48:63], v[160:163], v[176:179], v[48:63]
	s_waitcnt lgkmcnt(6)
	v_mfma_f32_32x32x16_bf16 v[16:31], v[160:163], v[180:183], v[16:31]
	v_mfma_f32_32x32x16_bf16 v[96:111], v[164:167], v[168:171], v[96:111]
	v_mfma_f32_32x32x16_bf16 v[64:79], v[164:167], v[172:175], v[64:79]
	v_mfma_f32_32x32x16_bf16 v[32:47], v[164:167], v[176:179], v[32:47]
	v_mfma_f32_32x32x16_bf16 v[0:15], v[164:167], v[180:183], v[0:15]
	s_waitcnt lgkmcnt(0)
	s_barrier
	s_add_u32 s2, s2, 0x80
	s_addc_u32 s3, s3, 0
	s_add_i32 s41, s41, 1
	s_cmpk_eq_i32 s2, 0x800
	s_cbranch_scc1 .Lkl_4
	s_and_b32 s12, s38, 2
	s_mul_i32 s12, s12, 0x9000
	s_add_i32 s12, s12, 0
	v_add3_u32 v197, s12, v196, v195
	v_add3_u32 v198, s12, v194, v195
	v_mfma_f32_32x32x16_bf16 v[112:127], v[202:205], v[210:213], v[112:127]
	v_mfma_f32_32x32x16_bf16 v[80:95], v[202:205], v[214:217], v[80:95]
	ds_read_b128 v[160:163], v197 offset:36864
	ds_read_b128 v[164:167], v198
	ds_read_b128 v[168:171], v198 offset:4608
	ds_read_b128 v[172:175], v198 offset:9216
	ds_read_b128 v[176:179], v198 offset:13824
	ds_read_b128 v[180:183], v197 offset:41472
	v_mfma_f32_32x32x16_bf16 v[48:63], v[202:205], v[224:227], v[48:63]
	v_mfma_f32_32x32x16_bf16 v[16:31], v[202:205], v[228:231], v[16:31]
	v_mfma_f32_32x32x16_bf16 v[96:111], v[206:209], v[210:213], v[96:111]
	v_mfma_f32_32x32x16_bf16 v[64:79], v[206:209], v[214:217], v[64:79]
	v_mfma_f32_32x32x16_bf16 v[32:47], v[206:209], v[224:227], v[32:47]
	v_mfma_f32_32x32x16_bf16 v[0:15], v[206:209], v[228:231], v[0:15]
	s_branch .Lkb_4
.Lkl_4:
	v_mfma_f32_32x32x16_bf16 v[112:127], v[202:205], v[210:213], v[112:127]
	v_mfma_f32_32x32x16_bf16 v[80:95], v[202:205], v[214:217], v[80:95]
	v_mfma_f32_32x32x16_bf16 v[48:63], v[202:205], v[224:227], v[48:63]
	v_mfma_f32_32x32x16_bf16 v[16:31], v[202:205], v[228:231], v[16:31]
	v_mfma_f32_32x32x16_bf16 v[96:111], v[206:209], v[210:213], v[96:111]
	v_mfma_f32_32x32x16_bf16 v[64:79], v[206:209], v[214:217], v[64:79]
	v_mfma_f32_32x32x16_bf16 v[32:47], v[206:209], v[224:227], v[32:47]
	v_mfma_f32_32x32x16_bf16 v[0:15], v[206:209], v[228:231], v[0:15]
	s_branch .LBB0_646

.LBB0_756:
.LBB0_757:
.LBB0_758:
	s_add_i32 s12, s16, -2
	s_and_b32 s12, s12, 2
	s_mul_i32 s12, s12, 0x9000
	s_add_i32 s12, s12, 0
	v_add3_u32 v200, s12, v199, v198
	v_add3_u32 v218, s12, v185, v198
	ds_read_b128 v[160:163], v200 offset:36864
	ds_read_b128 v[164:167], v218
	ds_read_b128 v[168:171], v218 offset:4608
	ds_read_b128 v[172:175], v218 offset:9216
	ds_read_b128 v[176:179], v218 offset:13824
	ds_read_b128 v[180:183], v200 offset:41472
.Lkb_5:
	s_waitcnt lgkmcnt(5)
	s_waitcnt lgkmcnt(4)
	v_mfma_f32_32x32x16_bf16 v[112:127], v[160:163], v[164:167], v[112:127]
	s_waitcnt lgkmcnt(3)
	v_mfma_f32_32x32x16_bf16 v[96:111], v[160:163], v[168:171], v[96:111]
	ds_read_b128 v[202:205], v200 offset:36896
	ds_read_b128 v[206:209], v218 offset:32
	ds_read_b128 v[210:213], v218 offset:4640
	ds_read_b128 v[214:217], v218 offset:9248
	ds_read_b128 v[224:227], v218 offset:13856
	ds_read_b128 v[228:231], v200 offset:41504
	s_waitcnt lgkmcnt(8)
	v_mfma_f32_32x32x16_bf16 v[80:95], v[160:163], v[172:175], v[80:95]
	s_waitcnt lgkmcnt(7)
	v_mfma_f32_32x32x16_bf16 v[48:63], v[160:163], v[176:179], v[48:63]
	s_waitcnt lgkmcnt(6)
	v_mfma_f32_32x32x16_bf16 v[64:79], v[180:183], v[164:167], v[64:79]
	v_mfma_f32_32x32x16_bf16 v[32:47], v[180:183], v[168:171], v[32:47]
	v_mfma_f32_32x32x16_bf16 v[16:31], v[180:183], v[172:175], v[16:31]
	v_mfma_f32_32x32x16_bf16 v[0:15], v[180:183], v[176:179], v[0:15]
	s_waitcnt lgkmcnt(0)
	s_and_b32 s12, s16, 2
	s_mul_i32 s12, s12, 0x9000
	s_add_i32 s12, s12, 0
	v_add_u32_e32 v220, s12, v194
	v_add_u32_e32 v219, s12, v184
	s_waitcnt vmcnt(7)
	ds_write_b128 v220, v[128:131]
	s_waitcnt vmcnt(6)
	ds_write_b128 v219, v[132:135] offset:36864
	v_add_u32_e32 v220, s12, v195
	s_waitcnt vmcnt(5)
	ds_write_b128 v220, v[136:139]
	s_waitcnt vmcnt(4)
	ds_write_b128 v219, v[140:143] offset:46080
	v_add_u32_e32 v220, s12, v196
	s_waitcnt vmcnt(3)
	ds_write_b128 v220, v[144:147]
	s_waitcnt vmcnt(2)
	ds_write_b128 v219, v[148:151] offset:55296
	v_add_u32_e32 v220, s12, v197
	s_waitcnt vmcnt(1)
	ds_write_b128 v220, v[152:155]
	s_waitcnt vmcnt(0)
	ds_write_b128 v219, v[156:159] offset:64512
	s_cmpk_gt_i32 s4, 0x680
	s_cbranch_scc1 .Lnl_4
	s_add_u32 s96, s92, s4
	s_addc_u32 s97, s93, s5
	s_add_u32 s98, s94, s4
	s_addc_u32 s99, s95, s5
	global_load_dwordx4 v[128:131], v248, s[96:97] offset:256
	global_load_dwordx4 v[132:135], v248, s[98:99] offset:256
	global_load_dwordx4 v[136:139], v249, s[96:97] offset:256
	global_load_dwordx4 v[140:143], v249, s[98:99] offset:256
	global_load_dwordx4 v[144:147], v250, s[96:97] offset:256
	global_load_dwordx4 v[148:151], v250, s[98:99] offset:256
	global_load_dwordx4 v[152:155], v251, s[96:97] offset:256
	global_load_dwordx4 v[156:159], v251, s[98:99] offset:256
.Lnl_4:
	v_mfma_f32_32x32x16_bf16 v[112:127], v[202:205], v[206:209], v[112:127]
	v_mfma_f32_32x32x16_bf16 v[96:111], v[202:205], v[210:213], v[96:111]
	ds_read_b128 v[160:163], v200 offset:36928
	ds_read_b128 v[164:167], v200 offset:41536
	ds_read_b128 v[168:171], v218 offset:64
	ds_read_b128 v[172:175], v218 offset:4672
	ds_read_b128 v[176:179], v218 offset:9280
	ds_read_b128 v[180:183], v218 offset:13888
	v_mfma_f32_32x32x16_bf16 v[80:95], v[202:205], v[214:217], v[80:95]
	v_mfma_f32_32x32x16_bf16 v[48:63], v[202:205], v[224:227], v[48:63]
	v_mfma_f32_32x32x16_bf16 v[64:79], v[228:231], v[206:209], v[64:79]
	v_mfma_f32_32x32x16_bf16 v[32:47], v[228:231], v[210:213], v[32:47]
	v_mfma_f32_32x32x16_bf16 v[16:31], v[228:231], v[214:217], v[16:31]
	v_mfma_f32_32x32x16_bf16 v[0:15], v[228:231], v[224:227], v[0:15]
	s_waitcnt lgkmcnt(5)
	s_waitcnt lgkmcnt(3)
	v_mfma_f32_32x32x16_bf16 v[112:127], v[160:163], v[168:171], v[112:127]
	s_waitcnt lgkmcnt(2)
	v_mfma_f32_32x32x16_bf16 v[96:111], v[160:163], v[172:175], v[96:111]
	ds_read_b128 v[202:205], v200 offset:36960
	ds_read_b128 v[206:209], v200 offset:41568
	ds_read_b128 v[210:213], v218 offset:96
	ds_read_b128 v[214:217], v218 offset:4704
	ds_read_b128 v[224:227], v218 offset:9312
	ds_read_b128 v[228:231], v218 offset:13920
	s_waitcnt lgkmcnt(7)
	v_mfma_f32_32x32x16_bf16 v[80:95], v[160:163], v[176:179], v[80:95]
	s_waitcnt lgkmcnt(6)
	v_mfma_f32_32x32x16_bf16 v[48:63], v[160:163], v[180:183], v[48:63]
	v_mfma_f32_32x32x16_bf16 v[64:79], v[164:167], v[168:171], v[64:79]
	v_mfma_f32_32x32x16_bf16 v[32:47], v[164:167], v[172:175], v[32:47]
	v_mfma_f32_32x32x16_bf16 v[16:31], v[164:167], v[176:179], v[16:31]
	v_mfma_f32_32x32x16_bf16 v[0:15], v[164:167], v[180:183], v[0:15]
	s_waitcnt lgkmcnt(0)
	s_barrier
	s_add_u32 s4, s4, 0x80
	s_addc_u32 s5, s5, 0
	s_add_i32 s16, s16, 2
	s_add_i32 s35, s35, 1
	s_cmpk_eq_i32 s4, 0x800
	s_cbranch_scc1 .Lkl_5
	s_add_i32 s12, s16, -2
	s_and_b32 s12, s12, 2
	s_mul_i32 s12, s12, 0x9000
	s_add_i32 s12, s12, 0
	v_add3_u32 v200, s12, v199, v198
	v_add3_u32 v218, s12, v185, v198
	v_mfma_f32_32x32x16_bf16 v[112:127], v[202:205], v[210:213], v[112:127]
	v_mfma_f32_32x32x16_bf16 v[96:111], v[202:205], v[214:217], v[96:111]
	ds_read_b128 v[160:163], v200 offset:36864
	ds_read_b128 v[164:167], v218
	ds_read_b128 v[168:171], v218 offset:4608
	ds_read_b128 v[172:175], v218 offset:9216
	ds_read_b128 v[176:179], v218 offset:13824
	ds_read_b128 v[180:183], v200 offset:41472
	v_mfma_f32_32x32x16_bf16 v[80:95], v[202:205], v[224:227], v[80:95]
	v_mfma_f32_32x32x16_bf16 v[48:63], v[202:205], v[228:231], v[48:63]
	v_mfma_f32_32x32x16_bf16 v[64:79], v[206:209], v[210:213], v[64:79]
	v_mfma_f32_32x32x16_bf16 v[32:47], v[206:209], v[214:217], v[32:47]
	v_mfma_f32_32x32x16_bf16 v[16:31], v[206:209], v[224:227], v[16:31]
	v_mfma_f32_32x32x16_bf16 v[0:15], v[206:209], v[228:231], v[0:15]
	s_branch .Lkb_5
.Lkl_5:
	v_mfma_f32_32x32x16_bf16 v[112:127], v[202:205], v[210:213], v[112:127]
	v_mfma_f32_32x32x16_bf16 v[96:111], v[202:205], v[214:217], v[96:111]
	v_mfma_f32_32x32x16_bf16 v[80:95], v[202:205], v[224:227], v[80:95]
	v_mfma_f32_32x32x16_bf16 v[48:63], v[202:205], v[228:231], v[48:63]
	v_mfma_f32_32x32x16_bf16 v[64:79], v[206:209], v[210:213], v[64:79]
	v_mfma_f32_32x32x16_bf16 v[32:47], v[206:209], v[214:217], v[32:47]
	v_mfma_f32_32x32x16_bf16 v[16:31], v[206:209], v[224:227], v[16:31]
	v_mfma_f32_32x32x16_bf16 v[0:15], v[206:209], v[228:231], v[0:15]
	s_branch .LBB0_761

.LBB0_797:
.LBB0_798:
.LBB0_799:
	s_add_i32 s12, s36, -2
	s_and_b32 s12, s12, 2
	s_mul_i32 s12, s12, 0x9000
	s_add_i32 s12, s12, 0
	v_add3_u32 v214, s12, v195, v194
	v_add3_u32 v215, s12, v193, v194
	ds_read_b128 v[160:163], v214 offset:36864
	ds_read_b128 v[164:167], v215
	ds_read_b128 v[168:171], v215 offset:4608
	ds_read_b128 v[172:175], v215 offset:9216
	ds_read_b128 v[176:179], v215 offset:13824
	ds_read_b128 v[180:183], v214 offset:41472
.Lkb_6:
	s_waitcnt lgkmcnt(5)
	s_waitcnt lgkmcnt(4)
	v_mfma_f32_32x32x16_bf16 v[112:127], v[160:163], v[164:167], v[112:127]
	s_waitcnt lgkmcnt(3)
	v_mfma_f32_32x32x16_bf16 v[96:111], v[160:163], v[168:171], v[96:111]
	ds_read_b128 v[196:199], v214 offset:36896
	ds_read_b128 v[202:205], v215 offset:32
	ds_read_b128 v[206:209], v215 offset:4640
	ds_read_b128 v[210:213], v215 offset:9248
	ds_read_b128 v[224:227], v215 offset:13856
	ds_read_b128 v[228:231], v214 offset:41504
	s_waitcnt lgkmcnt(8)
	v_mfma_f32_32x32x16_bf16 v[64:79], v[160:163], v[172:175], v[64:79]
	s_waitcnt lgkmcnt(7)
	v_mfma_f32_32x32x16_bf16 v[32:47], v[160:163], v[176:179], v[32:47]
	s_waitcnt lgkmcnt(6)
	v_mfma_f32_32x32x16_bf16 v[80:95], v[180:183], v[164:167], v[80:95]
	v_mfma_f32_32x32x16_bf16 v[48:63], v[180:183], v[168:171], v[48:63]
	v_mfma_f32_32x32x16_bf16 v[16:31], v[180:183], v[172:175], v[16:31]
	v_mfma_f32_32x32x16_bf16 v[0:15], v[180:183], v[176:179], v[0:15]
	s_waitcnt lgkmcnt(0)
	s_and_b32 s12, s36, 2
	s_mul_i32 s12, s12, 0x9000
	v_add_u32_e32 v216, s12, v192
	s_waitcnt vmcnt(7)
	ds_write_b128 v216, v[128:131]
	s_waitcnt vmcnt(6)
	ds_write_b128 v216, v[132:135] offset:36864
	s_waitcnt vmcnt(5)
	ds_write_b128 v216, v[136:139] offset:9216
	s_waitcnt vmcnt(4)
	ds_write_b128 v216, v[140:143] offset:46080
	s_waitcnt vmcnt(3)
	ds_write_b128 v216, v[144:147] offset:18432
	s_waitcnt vmcnt(2)
	ds_write_b128 v216, v[148:151] offset:55296
	s_waitcnt vmcnt(1)
	ds_write_b128 v216, v[152:155] offset:27648
	s_waitcnt vmcnt(0)
	ds_write_b128 v216, v[156:159] offset:64512
	s_cmpk_gt_i32 s4, 0x80
	s_cbranch_scc1 .Lnl_5
	s_add_u32 s96, s92, s4
	s_addc_u32 s97, s93, s5
	s_add_u32 s98, s94, s4
	s_addc_u32 s99, s95, s5
	global_load_dwordx4 v[128:131], v248, s[96:97] offset:256
	global_load_dwordx4 v[132:135], v248, s[98:99] offset:256
	global_load_dwordx4 v[136:139], v249, s[96:97] offset:256
	global_load_dwordx4 v[140:143], v249, s[98:99] offset:256
	global_load_dwordx4 v[144:147], v250, s[96:97] offset:256
	global_load_dwordx4 v[148:151], v250, s[98:99] offset:256
	global_load_dwordx4 v[152:155], v251, s[96:97] offset:256
	global_load_dwordx4 v[156:159], v251, s[98:99] offset:256
.Lnl_5:
	v_mfma_f32_32x32x16_bf16 v[112:127], v[196:199], v[202:205], v[112:127]
	v_mfma_f32_32x32x16_bf16 v[96:111], v[196:199], v[206:209], v[96:111]
	ds_read_b128 v[160:163], v214 offset:36928
	ds_read_b128 v[164:167], v214 offset:41536
	ds_read_b128 v[168:171], v215 offset:64
	ds_read_b128 v[172:175], v215 offset:4672
	ds_read_b128 v[176:179], v215 offset:9280
	ds_read_b128 v[180:183], v215 offset:13888
	v_mfma_f32_32x32x16_bf16 v[64:79], v[196:199], v[210:213], v[64:79]
	v_mfma_f32_32x32x16_bf16 v[32:47], v[196:199], v[224:227], v[32:47]
	v_mfma_f32_32x32x16_bf16 v[80:95], v[228:231], v[202:205], v[80:95]
	v_mfma_f32_32x32x16_bf16 v[48:63], v[228:231], v[206:209], v[48:63]
	v_mfma_f32_32x32x16_bf16 v[16:31], v[228:231], v[210:213], v[16:31]
	v_mfma_f32_32x32x16_bf16 v[0:15], v[228:231], v[224:227], v[0:15]
	s_waitcnt lgkmcnt(5)
	s_waitcnt lgkmcnt(3)
	v_mfma_f32_32x32x16_bf16 v[112:127], v[160:163], v[168:171], v[112:127]
	s_waitcnt lgkmcnt(2)
	v_mfma_f32_32x32x16_bf16 v[96:111], v[160:163], v[172:175], v[96:111]
	ds_read_b128 v[196:199], v214 offset:36960
	ds_read_b128 v[202:205], v214 offset:41568
	ds_read_b128 v[206:209], v215 offset:96
	ds_read_b128 v[210:213], v215 offset:4704
	ds_read_b128 v[224:227], v215 offset:9312
	ds_read_b128 v[228:231], v215 offset:13920
	s_waitcnt lgkmcnt(7)
	v_mfma_f32_32x32x16_bf16 v[64:79], v[160:163], v[176:179], v[64:79]
	s_waitcnt lgkmcnt(6)
	v_mfma_f32_32x32x16_bf16 v[32:47], v[160:163], v[180:183], v[32:47]
	v_mfma_f32_32x32x16_bf16 v[80:95], v[164:167], v[168:171], v[80:95]
	v_mfma_f32_32x32x16_bf16 v[48:63], v[164:167], v[172:175], v[48:63]
	v_mfma_f32_32x32x16_bf16 v[16:31], v[164:167], v[176:179], v[16:31]
	v_mfma_f32_32x32x16_bf16 v[0:15], v[164:167], v[180:183], v[0:15]
	s_waitcnt lgkmcnt(0)
	s_barrier
	s_add_u32 s4, s4, 0x80
	s_addc_u32 s5, s5, 0
	s_add_i32 s36, s36, 2
	s_add_i32 s17, s17, 1
	s_cmpk_lg_i32 s4, 0x200
	s_cbranch_scc0 .Lkl_6
	s_add_i32 s12, s36, -2
	s_and_b32 s12, s12, 2
	s_mul_i32 s12, s12, 0x9000
	s_add_i32 s12, s12, 0
	v_add3_u32 v214, s12, v195, v194
	v_add3_u32 v215, s12, v193, v194
	v_mfma_f32_32x32x16_bf16 v[112:127], v[196:199], v[206:209], v[112:127]
	v_mfma_f32_32x32x16_bf16 v[96:111], v[196:199], v[210:213], v[96:111]
	ds_read_b128 v[160:163], v214 offset:36864
	ds_read_b128 v[164:167], v215
	ds_read_b128 v[168:171], v215 offset:4608
	ds_read_b128 v[172:175], v215 offset:9216
	ds_read_b128 v[176:179], v215 offset:13824
	ds_read_b128 v[180:183], v214 offset:41472
	v_mfma_f32_32x32x16_bf16 v[64:79], v[196:199], v[224:227], v[64:79]
	v_mfma_f32_32x32x16_bf16 v[32:47], v[196:199], v[228:231], v[32:47]
	v_mfma_f32_32x32x16_bf16 v[80:95], v[202:205], v[206:209], v[80:95]
	v_mfma_f32_32x32x16_bf16 v[48:63], v[202:205], v[210:213], v[48:63]
	v_mfma_f32_32x32x16_bf16 v[16:31], v[202:205], v[224:227], v[16:31]
	v_mfma_f32_32x32x16_bf16 v[0:15], v[202:205], v[228:231], v[0:15]
	s_branch .Lkb_6
.Lkl_6:
	v_mfma_f32_32x32x16_bf16 v[112:127], v[196:199], v[206:209], v[112:127]
	v_mfma_f32_32x32x16_bf16 v[96:111], v[196:199], v[210:213], v[96:111]
	v_mfma_f32_32x32x16_bf16 v[64:79], v[196:199], v[224:227], v[64:79]
	v_mfma_f32_32x32x16_bf16 v[32:47], v[196:199], v[228:231], v[32:47]
	v_mfma_f32_32x32x16_bf16 v[80:95], v[202:205], v[206:209], v[80:95]
	v_mfma_f32_32x32x16_bf16 v[48:63], v[202:205], v[210:213], v[48:63]
	v_mfma_f32_32x32x16_bf16 v[16:31], v[202:205], v[224:227], v[16:31]
	v_mfma_f32_32x32x16_bf16 v[0:15], v[202:205], v[228:231], v[0:15]
	s_branch .LBB0_795

.LBB0_956:
.LBB0_957:
.LBB0_958:
	s_and_b32 s6, s34, 2
	s_mul_i32 s6, s6, 0x9000
	s_add_i32 s6, s6, 0
	v_add3_u32 v214, s6, v195, v200
	v_add3_u32 v215, s6, v194, v200
	ds_read_b128 v[160:163], v214 offset:36864
	ds_read_b128 v[164:167], v215
	ds_read_b128 v[168:171], v215 offset:4608
	ds_read_b128 v[172:175], v215 offset:9216
	ds_read_b128 v[176:179], v215 offset:13824
	ds_read_b128 v[180:183], v214 offset:41472
.Lkb_7:
	s_waitcnt lgkmcnt(5)
	s_waitcnt lgkmcnt(4)
	v_mfma_f32_32x32x16_bf16 v[112:127], v[160:163], v[164:167], v[112:127]
	s_waitcnt lgkmcnt(3)
	v_mfma_f32_32x32x16_bf16 v[80:95], v[160:163], v[168:171], v[80:95]
	ds_read_b128 v[196:199], v214 offset:36896
	ds_read_b128 v[202:205], v215 offset:32
	ds_read_b128 v[206:209], v215 offset:4640
	ds_read_b128 v[210:213], v215 offset:9248
	ds_read_b128 v[224:227], v215 offset:13856
	ds_read_b128 v[228:231], v214 offset:41504
	s_waitcnt lgkmcnt(8)
	v_mfma_f32_32x32x16_bf16 v[48:63], v[160:163], v[172:175], v[48:63]
	s_waitcnt lgkmcnt(7)
	v_mfma_f32_32x32x16_bf16 v[16:31], v[160:163], v[176:179], v[16:31]
	s_waitcnt lgkmcnt(6)
	v_mfma_f32_32x32x16_bf16 v[96:111], v[180:183], v[164:167], v[96:111]
	v_mfma_f32_32x32x16_bf16 v[64:79], v[180:183], v[168:171], v[64:79]
	v_mfma_f32_32x32x16_bf16 v[32:47], v[180:183], v[172:175], v[32:47]
	v_mfma_f32_32x32x16_bf16 v[0:15], v[180:183], v[176:179], v[0:15]
	s_waitcnt lgkmcnt(0)
	s_add_i32 s34, s34, 2
	s_and_b32 s6, s34, 2
	s_mul_i32 s6, s6, 0x9000
	v_add_u32_e32 v216, s6, v193
	s_waitcnt vmcnt(0)
	ds_write_b128 v216, v[128:131]
	ds_write_b128 v216, v[132:135] offset:36864
	ds_write_b128 v216, v[136:139] offset:9216
	ds_write_b128 v216, v[140:143] offset:46080
	ds_write_b128 v216, v[144:147] offset:18432
	ds_write_b128 v216, v[148:151] offset:55296
	ds_write_b128 v216, v[152:155] offset:27648
	ds_write_b128 v216, v[156:159] offset:64512
	s_cmpk_gt_i32 s2, 0x1480
	s_cbranch_scc1 .Lnl_8
	s_add_u32 s96, s92, s2
	s_addc_u32 s97, s93, s3
	s_add_u32 s98, s94, s2
	s_addc_u32 s99, s95, s3
	global_load_dwordx4 v[128:131], v248, s[96:97] offset:256
	global_load_dwordx4 v[132:135], v248, s[98:99] offset:256
	global_load_dwordx4 v[136:139], v249, s[96:97] offset:256
	global_load_dwordx4 v[140:143], v249, s[98:99] offset:256
	global_load_dwordx4 v[144:147], v250, s[96:97] offset:256
	global_load_dwordx4 v[148:151], v250, s[98:99] offset:256
	global_load_dwordx4 v[152:155], v251, s[96:97] offset:256
	global_load_dwordx4 v[156:159], v251, s[98:99] offset:256
.Lnl_8:
	v_mfma_f32_32x32x16_bf16 v[112:127], v[196:199], v[202:205], v[112:127]
	v_mfma_f32_32x32x16_bf16 v[80:95], v[196:199], v[206:209], v[80:95]
	ds_read_b128 v[160:163], v214 offset:36928
	ds_read_b128 v[164:167], v214 offset:41536
	ds_read_b128 v[168:171], v215 offset:64
	ds_read_b128 v[172:175], v215 offset:4672
	ds_read_b128 v[176:179], v215 offset:9280
	ds_read_b128 v[180:183], v215 offset:13888
	v_mfma_f32_32x32x16_bf16 v[48:63], v[196:199], v[210:213], v[48:63]
	v_mfma_f32_32x32x16_bf16 v[16:31], v[196:199], v[224:227], v[16:31]
	v_mfma_f32_32x32x16_bf16 v[96:111], v[228:231], v[202:205], v[96:111]
	v_mfma_f32_32x32x16_bf16 v[64:79], v[228:231], v[206:209], v[64:79]
	v_mfma_f32_32x32x16_bf16 v[32:47], v[228:231], v[210:213], v[32:47]
	v_mfma_f32_32x32x16_bf16 v[0:15], v[228:231], v[224:227], v[0:15]
	s_waitcnt lgkmcnt(5)
	s_waitcnt lgkmcnt(3)
	v_mfma_f32_32x32x16_bf16 v[112:127], v[160:163], v[168:171], v[112:127]
	s_waitcnt lgkmcnt(2)
	v_mfma_f32_32x32x16_bf16 v[80:95], v[160:163], v[172:175], v[80:95]
	ds_read_b128 v[196:199], v214 offset:36960
	ds_read_b128 v[202:205], v214 offset:41568
	ds_read_b128 v[206:209], v215 offset:96
	ds_read_b128 v[210:213], v215 offset:4704
	ds_read_b128 v[224:227], v215 offset:9312
	ds_read_b128 v[228:231], v215 offset:13920
	s_waitcnt lgkmcnt(7)
	v_mfma_f32_32x32x16_bf16 v[48:63], v[160:163], v[176:179], v[48:63]
	s_waitcnt lgkmcnt(6)
	v_mfma_f32_32x32x16_bf16 v[16:31], v[160:163], v[180:183], v[16:31]
	v_mfma_f32_32x32x16_bf16 v[96:111], v[164:167], v[168:171], v[96:111]
	v_mfma_f32_32x32x16_bf16 v[64:79], v[164:167], v[172:175], v[64:79]
	v_mfma_f32_32x32x16_bf16 v[32:47], v[164:167], v[176:179], v[32:47]
	v_mfma_f32_32x32x16_bf16 v[0:15], v[164:167], v[180:183], v[0:15]
	s_waitcnt lgkmcnt(0)
	s_barrier
	s_add_u32 s2, s2, 0x80
	s_addc_u32 s3, s3, 0
	s_add_i32 s39, s39, 1
	s_cmpk_eq_i32 s2, 0x1600
	s_cbranch_scc1 .Lkl_7
	s_and_b32 s6, s34, 2
	s_mul_i32 s6, s6, 0x9000
	s_add_i32 s6, s6, 0
	v_add3_u32 v214, s6, v195, v200
	v_add3_u32 v215, s6, v194, v200
	v_mfma_f32_32x32x16_bf16 v[112:127], v[196:199], v[206:209], v[112:127]
	v_mfma_f32_32x32x16_bf16 v[80:95], v[196:199], v[210:213], v[80:95]
	ds_read_b128 v[160:163], v214 offset:36864
	ds_read_b128 v[164:167], v215
	ds_read_b128 v[168:171], v215 offset:4608
	ds_read_b128 v[172:175], v215 offset:9216
	ds_read_b128 v[176:179], v215 offset:13824
	ds_read_b128 v[180:183], v214 offset:41472
	v_mfma_f32_32x32x16_bf16 v[48:63], v[196:199], v[224:227], v[48:63]
	v_mfma_f32_32x32x16_bf16 v[16:31], v[196:199], v[228:231], v[16:31]
	v_mfma_f32_32x32x16_bf16 v[96:111], v[202:205], v[206:209], v[96:111]
	v_mfma_f32_32x32x16_bf16 v[64:79], v[202:205], v[210:213], v[64:79]
	v_mfma_f32_32x32x16_bf16 v[32:47], v[202:205], v[224:227], v[32:47]
	v_mfma_f32_32x32x16_bf16 v[0:15], v[202:205], v[228:231], v[0:15]
	s_branch .Lkb_7

.LBB0_1047:
.LBB0_1048:
.LBB0_1049:
	s_add_i32 s12, s35, -2
	s_and_b32 s12, s12, 2
	s_mul_i32 s12, s12, 0x9000
	s_add_i32 s12, s12, 0
	v_add3_u32 v200, s12, v195, v191
	v_add3_u32 v214, s12, v190, v191
	ds_read_b128 v[160:163], v200 offset:36864
	ds_read_b128 v[164:167], v214
	ds_read_b128 v[168:171], v214 offset:4608
	ds_read_b128 v[172:175], v214 offset:9216
	ds_read_b128 v[176:179], v214 offset:13824
	ds_read_b128 v[180:183], v200 offset:41472
.Lkb_8:
	s_waitcnt lgkmcnt(5)
	s_waitcnt lgkmcnt(4)
	v_mfma_f32_32x32x16_bf16 v[112:127], v[160:163], v[164:167], v[112:127]
	s_waitcnt lgkmcnt(3)
	v_mfma_f32_32x32x16_bf16 v[80:95], v[160:163], v[168:171], v[80:95]
	ds_read_b128 v[196:199], v200 offset:36896
	ds_read_b128 v[202:205], v214 offset:32
	ds_read_b128 v[206:209], v214 offset:4640
	ds_read_b128 v[210:213], v214 offset:9248
	ds_read_b128 v[224:227], v214 offset:13856
	ds_read_b128 v[228:231], v200 offset:41504
	s_waitcnt lgkmcnt(8)
	v_mfma_f32_32x32x16_bf16 v[48:63], v[160:163], v[172:175], v[48:63]
	s_waitcnt lgkmcnt(7)
	v_mfma_f32_32x32x16_bf16 v[16:31], v[160:163], v[176:179], v[16:31]
	s_waitcnt lgkmcnt(6)
	v_mfma_f32_32x32x16_bf16 v[96:111], v[180:183], v[164:167], v[96:111]
	v_mfma_f32_32x32x16_bf16 v[64:79], v[180:183], v[168:171], v[64:79]
	v_mfma_f32_32x32x16_bf16 v[32:47], v[180:183], v[172:175], v[32:47]
	v_mfma_f32_32x32x16_bf16 v[0:15], v[180:183], v[176:179], v[0:15]
	s_waitcnt lgkmcnt(0)
	s_and_b32 s12, s35, 2
	s_mul_i32 s12, s12, 0x9000
	v_add_u32_e32 v215, s12, v189
	s_waitcnt vmcnt(7)
	ds_write_b128 v215, v[128:131]
	s_waitcnt vmcnt(6)
	ds_write_b128 v215, v[132:135] offset:36864
	s_waitcnt vmcnt(5)
	ds_write_b128 v215, v[136:139] offset:9216
	s_waitcnt vmcnt(4)
	ds_write_b128 v215, v[140:143] offset:46080
	s_waitcnt vmcnt(3)
	ds_write_b128 v215, v[144:147] offset:18432
	s_waitcnt vmcnt(2)
	ds_write_b128 v215, v[148:151] offset:55296
	s_waitcnt vmcnt(1)
	ds_write_b128 v215, v[152:155] offset:27648
	s_waitcnt vmcnt(0)
	ds_write_b128 v215, v[156:159] offset:64512
	s_cmpk_gt_i32 s2, 0x680
	s_cbranch_scc1 .Lnl_6
	s_add_u32 s96, s92, s2
	s_addc_u32 s97, s93, s3
	s_add_u32 s98, s94, s2
	s_addc_u32 s99, s95, s3
	global_load_dwordx4 v[128:131], v248, s[96:97] offset:256
	global_load_dwordx4 v[132:135], v248, s[98:99] offset:256
	global_load_dwordx4 v[136:139], v249, s[96:97] offset:256
	global_load_dwordx4 v[140:143], v249, s[98:99] offset:256
	global_load_dwordx4 v[144:147], v250, s[96:97] offset:256
	global_load_dwordx4 v[148:151], v250, s[98:99] offset:256
	global_load_dwordx4 v[152:155], v251, s[96:97] offset:256
	global_load_dwordx4 v[156:159], v251, s[98:99] offset:256
.Lnl_6:
	v_mfma_f32_32x32x16_bf16 v[112:127], v[196:199], v[202:205], v[112:127]
	v_mfma_f32_32x32x16_bf16 v[80:95], v[196:199], v[206:209], v[80:95]
	ds_read_b128 v[160:163], v200 offset:36928
	ds_read_b128 v[164:167], v200 offset:41536
	ds_read_b128 v[168:171], v214 offset:64
	ds_read_b128 v[172:175], v214 offset:4672
	ds_read_b128 v[176:179], v214 offset:9280
	ds_read_b128 v[180:183], v214 offset:13888
	v_mfma_f32_32x32x16_bf16 v[48:63], v[196:199], v[210:213], v[48:63]
	v_mfma_f32_32x32x16_bf16 v[16:31], v[196:199], v[224:227], v[16:31]
	v_mfma_f32_32x32x16_bf16 v[96:111], v[228:231], v[202:205], v[96:111]
	v_mfma_f32_32x32x16_bf16 v[64:79], v[228:231], v[206:209], v[64:79]
	v_mfma_f32_32x32x16_bf16 v[32:47], v[228:231], v[210:213], v[32:47]
	v_mfma_f32_32x32x16_bf16 v[0:15], v[228:231], v[224:227], v[0:15]
	s_waitcnt lgkmcnt(5)
	s_waitcnt lgkmcnt(3)
	v_mfma_f32_32x32x16_bf16 v[112:127], v[160:163], v[168:171], v[112:127]
	s_waitcnt lgkmcnt(2)
	v_mfma_f32_32x32x16_bf16 v[80:95], v[160:163], v[172:175], v[80:95]
	ds_read_b128 v[196:199], v200 offset:36960
	ds_read_b128 v[202:205], v200 offset:41568
	ds_read_b128 v[206:209], v214 offset:96
	ds_read_b128 v[210:213], v214 offset:4704
	ds_read_b128 v[224:227], v214 offset:9312
	ds_read_b128 v[228:231], v214 offset:13920
	s_waitcnt lgkmcnt(7)
	v_mfma_f32_32x32x16_bf16 v[48:63], v[160:163], v[176:179], v[48:63]
	s_waitcnt lgkmcnt(6)
	v_mfma_f32_32x32x16_bf16 v[16:31], v[160:163], v[180:183], v[16:31]
	v_mfma_f32_32x32x16_bf16 v[96:111], v[164:167], v[168:171], v[96:111]
	v_mfma_f32_32x32x16_bf16 v[64:79], v[164:167], v[172:175], v[64:79]
	v_mfma_f32_32x32x16_bf16 v[32:47], v[164:167], v[176:179], v[32:47]
	v_mfma_f32_32x32x16_bf16 v[0:15], v[164:167], v[180:183], v[0:15]
	s_waitcnt lgkmcnt(0)
	s_barrier
	s_add_u32 s2, s2, 0x80
	s_addc_u32 s3, s3, 0
	s_add_i32 s35, s35, 2
	s_add_i32 s16, s16, 1
	s_cmpk_eq_i32 s2, 0x800
	s_cbranch_scc1 .Lkl_8
	s_add_i32 s12, s35, -2
	s_and_b32 s12, s12, 2
	s_mul_i32 s12, s12, 0x9000
	s_add_i32 s12, s12, 0
	v_add3_u32 v200, s12, v195, v191
	v_add3_u32 v214, s12, v190, v191
	v_mfma_f32_32x32x16_bf16 v[112:127], v[196:199], v[206:209], v[112:127]
	v_mfma_f32_32x32x16_bf16 v[80:95], v[196:199], v[210:213], v[80:95]
	ds_read_b128 v[160:163], v200 offset:36864
	ds_read_b128 v[164:167], v214
	ds_read_b128 v[168:171], v214 offset:4608
	ds_read_b128 v[172:175], v214 offset:9216
	ds_read_b128 v[176:179], v214 offset:13824
	ds_read_b128 v[180:183], v200 offset:41472
	v_mfma_f32_32x32x16_bf16 v[48:63], v[196:199], v[224:227], v[48:63]
	v_mfma_f32_32x32x16_bf16 v[16:31], v[196:199], v[228:231], v[16:31]
	v_mfma_f32_32x32x16_bf16 v[96:111], v[202:205], v[206:209], v[96:111]
	v_mfma_f32_32x32x16_bf16 v[64:79], v[202:205], v[210:213], v[64:79]
	v_mfma_f32_32x32x16_bf16 v[32:47], v[202:205], v[224:227], v[32:47]
	v_mfma_f32_32x32x16_bf16 v[0:15], v[202:205], v[228:231], v[0:15]
	s_branch .Lkb_8
